# Griffin: conv-row LDS staging published by the existing pre-output barrier (one block barrier fewer per tile)
# speedup vs baseline: 1.0269x; 1.0015x over previous
.LBB0_483:
	s_waitcnt vmcnt(0)
	v_mul_u32_u24_e32 v224, 0x110, v233
	v_lshl_add_u32 v224, v232, 4, v224
	ds_write_b128 v224, v[2:5] offset:47360
	ds_write_b128 v224, v[6:9] offset:51712
	ds_write_b128 v224, v[10:13] offset:56064
	ds_write_b128 v224, v[14:17] offset:60416
	v_cmp_gt_u32_e32 vcc, 3, v233
	s_and_saveexec_b64 s[28:29], vcc
	s_cbranch_execz .Lgx_skipw5
	ds_write_b128 v224, v[18:21] offset:64768

.Lgr_latch_common:
	s_cmp_eq_u32 s45, 64
	s_mov_b32 s16, s45
	v_mul_u32_u24_e32 v224, 0x110, v228
	v_and_b32_e32 v225, 3, v232
	v_lshl_add_u32 v224, v225, 6, v224
	ds_read_b64 v[160:161], v224 offset:47360
	ds_read_b64 v[162:163], v224 offset:47632
	ds_read_b64 v[164:165], v224 offset:47904
	ds_read_b64 v[166:167], v224 offset:48176
	ds_read_b64 v[168:169], v224 offset:47368
	ds_read_b64 v[170:171], v224 offset:47640
	ds_read_b64 v[172:173], v224 offset:47912
	ds_read_b64 v[174:175], v224 offset:47376
	ds_read_b64 v[176:177], v224 offset:48184
	ds_read_b64 v[178:179], v224 offset:47648
	ds_read_b64 v[180:181], v224 offset:47920
	ds_read_b64 v[182:183], v224 offset:48192
	s_waitcnt lgkmcnt(0)
	ds_read_b64 v[184:185], v224 offset:47384
	ds_read_b64 v[186:187], v224 offset:47656
	ds_read_b64 v[188:189], v224 offset:47928
	ds_read_b64 v[190:191], v224 offset:47392
	ds_read_b64 v[192:193], v224 offset:48200
	ds_read_b64 v[194:195], v224 offset:47664
	ds_read_b64 v[196:197], v224 offset:47936
	ds_read_b64 v[198:199], v224 offset:48208
	ds_read_b64 v[200:201], v224 offset:47400
	ds_read_b64 v[202:203], v224 offset:47672
	ds_read_b64 v[204:205], v224 offset:47944
	ds_read_b64 v[206:207], v224 offset:47408
	s_waitcnt lgkmcnt(0)
	ds_read_b64 v[208:209], v224 offset:48216
	ds_read_b64 v[210:211], v224 offset:47680
	ds_read_b64 v[212:213], v224 offset:47952
	ds_read_b64 v[214:215], v224 offset:48224
	ds_read_b64 v[216:217], v224 offset:47416
	ds_read_b64 v[218:219], v224 offset:47688
	ds_read_b64 v[220:221], v224 offset:47960
	ds_read_b64 v[222:223], v224 offset:48232
	s_waitcnt lgkmcnt(0)
	s_cmp_eq_u32 s45, 64
	s_cbranch_scc1 .LBB0_470

.LBB0_527:
	s_or_b64 exec, exec, s[28:29]
	v_mov_b32_e32 v75, v233
	v_mov_b32_e32 v76, v232
	s_lshl_b32 s16, s16, 6
	s_waitcnt vmcnt(0)
	v_mul_u32_u24_e32 v224, 0x110, v233
	v_lshl_add_u32 v224, v232, 4, v224
	ds_write_b128 v224, v[2:5] offset:47360
	ds_write_b128 v224, v[6:9] offset:51712
	ds_write_b128 v224, v[10:13] offset:56064
	ds_write_b128 v224, v[14:17] offset:60416
	v_cmp_gt_u32_e32 vcc, 3, v233
	s_and_saveexec_b64 s[28:29], vcc
	s_cbranch_execz .Lgx_skipw5b
	ds_write_b128 v224, v[18:21] offset:64768
.Lgx_skipw5b:
	s_or_b64 exec, exec, s[28:29]
	s_waitcnt lgkmcnt(0)
	s_barrier
	v_lshlrev_b32_e32 v250, 16, v250
	v_lshlrev_b32_e32 v251, 16, v251
	v_lshlrev_b32_e32 v157, 16, v157
	v_lshlrev_b32_e32 v249, 16, v249
	s_add_u32 s28, s22, s16
	v_lshlrev_b32_e32 v78, 2, v75
	s_addc_u32 s29, s23, 0
	v_ashrrev_i32_e32 v79, 31, v78
	v_lshl_add_u64 v[78:79], s[28:29], 0, v[78:79]
	v_fma_f32 v68, v72, v74, v68
	v_lshlrev_b64 v[78:79], 11, v[78:79]
	v_mul_f32_e32 v72, v251, v68
	v_lshl_add_u64 v[78:79], s[26:27], 0, v[78:79]
	v_ashrrev_i32_e32 v77, 31, v76
	v_bfe_u32 v74, v72, 16, 1
	v_fmac_f32_e32 v69, v73, v68
	v_lshl_add_u64 v[76:77], v[76:77], 1, v[78:79]
	v_add3_u32 v72, v72, v74, s43
	v_mul_f32_e32 v68, v250, v69
	global_store_short_d16_hi v[76:77], v72, off
	v_bfe_u32 v72, v68, 16, 1
	v_add3_u32 v68, v68, v72, s43
	v_fma_f32 v66, v70, v69, v66
	global_store_short_d16_hi v[76:77], v68, off offset:2048
	v_mul_f32_e32 v68, v249, v66
	v_bfe_u32 v69, v68, 16, 1
	v_add3_u32 v70, v68, v69, s43
	v_add_co_u32_e32 v68, vcc, 0x1000, v76
	v_fmac_f32_e32 v67, v71, v66
	s_nop 0
	v_addc_co_u32_e32 v69, vcc, 0, v77, vcc
	v_mul_f32_e32 v66, v157, v67
	global_store_short_d16_hi v[68:69], v70, off
	v_bfe_u32 v70, v66, 16, 1
	v_add3_u32 v66, v66, v70, s43
	global_store_short_d16_hi v[68:69], v66, off offset:2048
	s_and_saveexec_b64 s[28:29], s[12:13]
	s_cbranch_execz .LBB0_482
	ds_write_b32 v239, v67 offset:20544
	s_branch .LBB0_482
